# attention tile loop: one static s_setprio 1 for waves 4-7 before the loop, all per-segment priority flips removed
# baseline (speedup 1.0000x reference)
; #define LAS __attribute__((address_space(3)))
; __device__ __forceinline__ void attn_unit(const TI ti, CArgs& a, int b, int hd, int qrow0, int st_lo, int st_hi, float mfix, float lam, float lam_init, const float* subg, unsigned char* ldsg) {
;     const int tid = ti.tid, lane = tid & 63, w = tid >> 6, r = lane & 31, h = lane >> 5, qt = w >> 1, c = w & 1;
;     bf16_t* Qb = (bf16_t*)(a.ws + WS_Q); const bf16_t* Kb = (const bf16_t*)(a.ws + WS_K); const bf16_t* Vb = (const bf16_t*)(a.ws + WS_V);
;     LAS unsigned char* L = (LAS unsigned char*)ldsg;
;     constexpr int KOFF = 0, VOFF = 17408, BUFB = 35840;
;     bf16x8 qf[4];
;     { const bf16_t* qp = Qb + (size_t)(qrow0 + qt * 32 + r) * 1024 + hd * 128 + c * 64 + 8 * h;
; #pragma unroll
;       for (int ks = 0; ks < 4; ++ks) qf[ks] = *(const bf16x8*)(qp + 16 * ks); }
;     f32x16 O[4];
; #pragma unroll
;     for (int e = 0; e < 4; ++e)
; #pragma unroll
;         for (int i = 0; i < 16; ++i) O[e][i] = 0.f;
;     float lsum = 0.f;
;     u32x4 kreg[2], vreg[2];
;     typedef const __attribute__((address_space(1))) u32x4* gc16_t;
;     const int koff0 = (tid >> 4) * 1024 + (tid & 15) * 8, koff1 = koff0 + 32 * 1024, voff = lane * 1024 + w * 16;
;     ...
;     ATT_LOAD(st_lo); ATT_STORE(0);
;     __syncthreads();
.LBB0_349:
	s_and_b64 vcc, exec, s[4:5]
	s_cbranch_vccz .LBB0_332
	s_ashr_i32 s5, s16, 7
	s_lshl_b32 s4, s5, 11
	s_and_b32 s17, s17, 0x780
	s_or_b32 s17, s4, s17
	v_add_u32_e32 v18, s17, v139
	v_ashrrev_i32_e32 v19, 31, v18
	s_lshl_b32 s17, s16, 4
	s_lshl_b32 s33, s5, 8
	s_ashr_i32 s5, s4, 31
	v_lshlrev_b64 v[18:19], 11, v[18:19]
	s_and_b32 s18, s17, 0x700
	s_lshl_b64 s[34:35], s[4:5], 11
	v_lshl_add_u64 v[18:19], s[46:47], 0, v[18:19]
	s_add_u32 s5, s3, s34
	v_lshl_add_u64 v[152:153], v[18:19], 0, s[18:19]
	s_addc_u32 s17, s6, s35
	v_lshl_add_u64 v[18:19], v[152:153], 0, v[0:1]
	v_mov_b32_e32 v151, v1
	s_add_u32 s5, s5, s18
	v_lshl_add_u64 v[18:19], v[18:19], 0, v[150:151]
	s_addc_u32 s17, s17, 0
	global_load_dwordx4 v[110:113], v[18:19], off
	global_load_dwordx4 v[106:109], v[18:19], off offset:32
	global_load_dwordx4 v[102:105], v[18:19], off offset:64
	global_load_dwordx4 v[98:101], v[18:19], off offset:96
	v_mov_b32_e32 v18, s5
	v_mov_b32_e32 v19, s17
	v_lshl_add_u64 v[22:23], v[140:141], 1, v[18:19]
	global_load_dwordx4 v[18:21], v[22:23], off
	v_add_co_u32_e32 v22, vcc, s79, v22
	s_add_u32 s5, s7, s34
	s_nop 0
	v_addc_co_u32_e32 v23, vcc, 0, v23, vcc
	global_load_dwordx4 v[22:25], v[22:23], off
	s_addc_u32 s17, s10, s35
	s_add_u32 s5, s5, s18
	s_addc_u32 s17, s17, 0
	v_mov_b32_e32 v26, s5
	v_mov_b32_e32 v27, s17
	v_lshl_add_u64 v[26:27], v[142:143], 1, v[26:27]
	s_add_u32 s27, s3, s18
	s_addc_u32 s34, s6, 0
	s_add_u32 s18, s7, s18
	v_mov_b32_e32 v0, 0
	s_mov_b32 s17, 0
	s_addc_u32 s35, s10, 0
	s_add_i32 s37, s33, 0x3840
	s_or_b32 s39, s4, 64
	v_mov_b32_e32 v28, v0
	v_mov_b32_e32 v29, v0
	v_mov_b32_e32 v30, v0
	v_mov_b32_e32 v31, v0
	v_mov_b32_e32 v32, v0
	v_mov_b32_e32 v33, v0
	v_mov_b32_e32 v34, 0
	v_mov_b32_e32 v35, v0
	v_mov_b32_e32 v36, v0
	v_mov_b32_e32 v37, v0
	v_mov_b32_e32 v38, v0
	v_mov_b32_e32 v39, v0
	v_mov_b32_e32 v40, v0
	v_mov_b32_e32 v41, v0
	v_mov_b32_e32 v42, v0
	v_mov_b32_e32 v43, v0
	v_mov_b32_e32 v44, v0
	v_mov_b32_e32 v45, v0
	v_mov_b32_e32 v46, v0
	v_mov_b32_e32 v47, v0
	v_mov_b32_e32 v48, v0
	v_mov_b32_e32 v49, v0
	v_mov_b32_e32 v66, 0
	v_mov_b32_e32 v67, v0
	v_mov_b32_e32 v68, v0
	v_mov_b32_e32 v69, v0
	v_mov_b32_e32 v70, v0
	v_mov_b32_e32 v71, v0
	v_mov_b32_e32 v72, v0
	v_mov_b32_e32 v73, v0
	v_mov_b32_e32 v74, v0
	v_mov_b32_e32 v75, v0
	v_mov_b32_e32 v76, v0
	v_mov_b32_e32 v77, v0
	v_mov_b32_e32 v78, v0
	v_mov_b32_e32 v79, v0
	v_mov_b32_e32 v80, v0
	v_mov_b32_e32 v81, v0
	v_mov_b32_e32 v50, 0
	v_mov_b32_e32 v51, v0
	v_mov_b32_e32 v52, v0
	v_mov_b32_e32 v53, v0
	v_mov_b32_e32 v54, v0
	v_mov_b32_e32 v55, v0
	v_mov_b32_e32 v56, v0
	v_mov_b32_e32 v57, v0
	v_mov_b32_e32 v58, v0
	s_waitcnt vmcnt(1)
	ds_write_b128 v169, v[18:21]
	s_waitcnt vmcnt(0)
	ds_write_b128 v170, v[22:25]
	global_load_dwordx4 v[18:21], v[26:27], off
	v_mov_b32_e32 v59, v0
	v_mov_b32_e32 v60, v0
	v_mov_b32_e32 v61, v0
	v_mov_b32_e32 v62, v0
	v_mov_b32_e32 v63, v0
	v_mov_b32_e32 v64, v0
	v_mov_b32_e32 v65, v0
	s_waitcnt vmcnt(0)
	ds_write_b16 v159, v18 offset:17408
	ds_write_b16_d16_hi v159, v18 offset:17552
	global_load_dwordx4 v[22:25], v[26:27], off offset:16
	v_mov_b32_e32 v18, 0
	v_mov_b32_e32 v26, v0
	v_mov_b32_e32 v27, v0
	s_waitcnt vmcnt(0)
	ds_write_b16 v159, v22 offset:18560
	ds_write_b16_d16_hi v159, v22 offset:18704
	ds_write_b16 v159, v19 offset:17696
	ds_write_b16_d16_hi v159, v19 offset:17840
	ds_write_b16 v159, v23 offset:18848
	ds_write_b16_d16_hi v159, v23 offset:18992
	ds_write_b16 v159, v20 offset:17984
	ds_write_b16_d16_hi v159, v20 offset:18128
	ds_write_b16 v159, v24 offset:19136
	ds_write_b16_d16_hi v159, v24 offset:19280
	ds_write_b16 v159, v21 offset:18272
	ds_write_b16_d16_hi v159, v21 offset:18416
	ds_write_b16 v159, v25 offset:19424
	ds_write_b16_d16_hi v159, v25 offset:19568
	v_mov_b32_e32 v19, v0
	v_mov_b32_e32 v20, v0
	v_mov_b32_e32 v21, v0
	v_mov_b32_e32 v22, v0
	v_mov_b32_e32 v23, v0
	v_mov_b32_e32 v24, v0
	v_mov_b32_e32 v25, v0
	s_waitcnt lgkmcnt(0)
	s_barrier
	s_cmp_lg_u64 s[40:41], 0
	s_cbranch_scc0 .Lattn_prio_lead
	s_setprio 1

; __device__ __forceinline__ void attn_unit(const TI ti, CArgs& a, int b, int hd, int qrow0, int st_lo, int st_hi, float mfix, float lam, float lam_init, const float* subg, unsigned char* ldsg) {
;     ...
;     ATT_LOAD(st_lo); ATT_STORE(0);
;     __syncthreads();
;     for (int st = st_lo; st < st_hi; ++st) {
;         const int bi = (st - st_lo) & 1;
;         if (st + 1 < st_hi) ATT_LOAD(st + 1);
;     ...
;         if (st + 1 < st_hi) ATT_STORE(bi ^ 1);
;         __syncthreads();
.LBB0_351:
	s_or_b64 exec, exec, s[4:5]
	s_add_i32 s17, s17, 1
	s_xor_b32 s4, s48, 1
	s_mul_i32 s4, s4, 0x8c00
	s_add_i32 s4, s4, 0
	v_add_u32_e32 v82, s4, v147
	v_add_u32_e32 v83, v82, v155
	v_add_u32_e32 v82, v82, v156
	s_add_i32 s37, s37, 64
	s_add_i32 s39, s39, 64
	s_waitcnt vmcnt(3)
	ds_write_b128 v83, v[122:125]
	s_waitcnt vmcnt(2)
	ds_write_b128 v82, v[126:129]
	v_add3_u32 v82, s4, v157, v158
	s_cmp_eq_u32 s17, 35
	s_waitcnt vmcnt(1)
	ds_write_b16 v82, v118 offset:17408
	ds_write_b16_d16_hi v82, v118 offset:17552
	s_waitcnt vmcnt(0)
	ds_write_b16 v82, v114 offset:18560
	ds_write_b16_d16_hi v82, v114 offset:18704
	ds_write_b16 v82, v119 offset:17696
	ds_write_b16_d16_hi v82, v119 offset:17840
	ds_write_b16 v82, v115 offset:18848
	ds_write_b16_d16_hi v82, v115 offset:18992
	ds_write_b16 v82, v120 offset:17984
	ds_write_b16_d16_hi v82, v120 offset:18128
	ds_write_b16 v82, v116 offset:19136
	ds_write_b16_d16_hi v82, v116 offset:19280
	ds_write_b16 v82, v121 offset:18272
	ds_write_b16_d16_hi v82, v121 offset:18416
	ds_write_b16 v82, v117 offset:19424
	ds_write_b16_d16_hi v82, v117 offset:19568
	s_waitcnt lgkmcnt(0)
	s_cmp_eq_u32 s17, 35
	s_cbranch_scc1 .Lattn_last
	s_cmp_lt_u32 s17, 31
	s_cselect_b32 s4, s39, s37
	s_ashr_i32 s5, s4, 31
	s_lshl_b64 s[4:5], s[4:5], 11
	s_add_u32 s33, s27, s4
	s_addc_u32 s36, s34, s5
	v_mov_b32_e32 v82, s33
	v_mov_b32_e32 v83, s36
	s_add_u32 s4, s18, s4
	s_addc_u32 s5, s35, s5
	v_lshl_add_u64 v[82:83], v[140:141], 1, v[82:83]
	v_mov_b32_e32 v84, s4
	v_mov_b32_e32 v85, s5
	v_add_co_u32_e32 v86, vcc, s79, v82
	s_nop 0
	v_addc_co_u32_e32 v87, vcc, 0, v83, vcc
	global_load_dwordx4 v[122:125], v[82:83], off
	global_load_dwordx4 v[126:129], v[86:87], off
	v_lshl_add_u64 v[82:83], v[142:143], 1, v[84:85]
	global_load_dwordx4 v[118:121], v[82:83], off
	global_load_dwordx4 v[114:117], v[82:83], off offset:16
	s_and_b32 s48, s17, 1
	s_mul_i32 s4, s48, 0x8c00
	s_add_i32 s4, s4, 0
	v_add_u32_e32 v82, s4, v160
	v_add_u32_e32 v151, v82, v161
	v_add3_u32 v150, s4, v144, v162
	s_barrier
	s_branch .Lattn_body

; #define LAS __attribute__((address_space(3)))
; #define ATT_QK(SX, sub) do { __builtin_amdgcn_s_setprio(1); _Pragma("unroll") for (int ks = 0; ks < 4; ++ks) { \
;             const bf16x8 kf = *(LAS const bf16x8*)(Bb + KOFF + ((sub) * 32 + r) * 272 + (c * 64 + 16 * ks + 8 * h) * 2); SX = MFMA32(kf, qf[ks], SX); } __builtin_amdgcn_s_setprio(0); } while (0)
; #define ATT_SOFT(SX, P0, P1) do { float p[16]; _Pragma("unroll") for (int i = 0; i < 16; ++i) { p[i] = __builtin_amdgcn_exp2f(SX[i]); lsum += p[i]; } \
;             P0 = pk8f(p[0], p[1], p[2], p[3], p[4], p[5], p[6], p[7]); P1 = pk8f(p[8], p[9], p[10], p[11], p[12], p[13], p[14], p[15]); } while (0)
; #define ATT_PV(sub, P0, P1) do { __builtin_amdgcn_s_setprio(1); _Pragma("unroll") for (int et = 0; et < 4; ++et) { _Pragma("unroll") for (int s = 0; s < 2; ++s) { \
;             const bf16x8 vf = *(LAS const bf16x8*)(Bb + VOFF + (et * 32 + r) * 144 + ((sub) * 32 + 16 * s + 8 * h) * 2); O[et] = MFMA32(vf, s ? P1 : P0, O[et]); } } __builtin_amdgcn_s_setprio(0); } while (0)
; __device__ __forceinline__ void attn_unit(const TI ti, CArgs& a, int b, int hd, int qrow0, int st_lo, int st_hi, float mfix, float lam, float lam_init, const float* subg, unsigned char* ldsg) {
;     ...
;         LAS const unsigned char* Bb = L + bi * BUFB;
;         f32x16 Sx0, Sx1; bf16x8 pa0, pa1, pc0, pc1;
; #pragma unroll
;         for (int i = 0; i < 16; ++i) { Sx0[i] = -mfix; Sx1[i] = -mfix; }
;     ...
;         if (w < 4) {
;             ATT_QK(Sx0, 0); ATT_QK(Sx1, 1);
;             __builtin_amdgcn_sched_barrier(0);
;             ATT_SOFT(Sx0, pa0, pa1); ATT_PV(0, pa0, pa1);
;             ATT_SOFT(Sx1, pc0, pc1); ATT_PV(1, pc0, pc1);
.Lattn_body:
	ds_read_b128 v[130:133], v151
	s_and_saveexec_b64 s[4:5], s[40:41]
	s_xor_b64 s[4:5], exec, s[4:5]
	s_cbranch_execz .LBB0_354
	ds_read_b128 v[182:185], v151 offset:32
	ds_read_b128 v[198:201], v151 offset:64
	ds_read_b128 v[202:205], v151 offset:96
	ds_read_b128 v[206:209], v151 offset:8704
	ds_read_b128 v[210:213], v151 offset:8736
	ds_read_b128 v[236:239], v151 offset:8768
	ds_read_b128 v[240:243], v151 offset:8800
	s_waitcnt lgkmcnt(7)
	v_mfma_f32_32x32x16_bf16 v[82:97], v[130:133], v[110:113], v[2:17]
	s_waitcnt lgkmcnt(6)
	v_mfma_f32_32x32x16_bf16 v[82:97], v[182:185], v[106:109], v[82:97]
	s_waitcnt lgkmcnt(5)
	v_mfma_f32_32x32x16_bf16 v[82:97], v[198:201], v[102:105], v[82:97]
	s_waitcnt lgkmcnt(4)
	v_mfma_f32_32x32x16_bf16 v[82:97], v[202:205], v[98:101], v[82:97]
	ds_read_b128 v[130:133], v150 offset:17408
	ds_read_b128 v[182:185], v150 offset:17440
	ds_read_b128 v[198:201], v150 offset:22016
	ds_read_b128 v[202:205], v150 offset:22048
	s_waitcnt lgkmcnt(7)
	v_mfma_f32_32x32x16_bf16 v[220:235], v[206:209], v[110:113], v[2:17]
	s_waitcnt lgkmcnt(6)
	v_mfma_f32_32x32x16_bf16 v[220:235], v[210:213], v[106:109], v[220:235]
	s_waitcnt lgkmcnt(5)
	v_mfma_f32_32x32x16_bf16 v[220:235], v[236:239], v[102:105], v[220:235]
	s_waitcnt lgkmcnt(4)
	v_mfma_f32_32x32x16_bf16 v[220:235], v[240:243], v[98:101], v[220:235]
	ds_read_b128 v[206:209], v150 offset:26624
	ds_read_b128 v[210:213], v150 offset:26656
	ds_read_b128 v[236:239], v150 offset:31232
	ds_read_b128 v[240:243], v150 offset:31264
	v_exp_f32_e32 v169, v82
	v_exp_f32_e32 v170, v83
	v_exp_f32_e32 v171, v84
	v_exp_f32_e32 v174, v85
	v_exp_f32_e32 v175, v86
	v_exp_f32_e32 v176, v87
	v_exp_f32_e32 v177, v88
	v_exp_f32_e32 v179, v89
	v_exp_f32_e32 v90, v90
	v_exp_f32_e32 v91, v91
	v_exp_f32_e32 v92, v92
	v_exp_f32_e32 v93, v93
	v_exp_f32_e32 v94, v94
	v_exp_f32_e32 v95, v95
	v_exp_f32_e32 v96, v96
	v_exp_f32_e32 v97, v97
	v_cvt_pk_bf16_f32 v82, v169, v170
	v_cvt_pk_bf16_f32 v83, v171, v174
	v_cvt_pk_bf16_f32 v84, v175, v176
	v_cvt_pk_bf16_f32 v85, v177, v179
	v_cvt_pk_bf16_f32 v86, v90, v91
	v_cvt_pk_bf16_f32 v87, v92, v93
	v_cvt_pk_bf16_f32 v88, v94, v95
	v_cvt_pk_bf16_f32 v89, v96, v97
	s_waitcnt lgkmcnt(7)
	v_mfma_f32_32x32x16_bf16 v[18:33], v[130:133], v[82:85], v[18:33]
	v_add_f32_e32 v0, v169, v0
	v_add_f32_e32 v0, v170, v0
	s_waitcnt lgkmcnt(6)
	v_mfma_f32_32x32x16_bf16 v[18:33], v[182:185], v[86:89], v[18:33]
	v_add_f32_e32 v0, v171, v0
	v_add_f32_e32 v0, v174, v0
	ds_read_b128 v[130:133], v150 offset:17472
	ds_read_b128 v[182:185], v150 offset:17504
	s_waitcnt lgkmcnt(7)
	v_mfma_f32_32x32x16_bf16 v[34:49], v[198:201], v[82:85], v[34:49]
	v_add_f32_e32 v0, v175, v0
	v_add_f32_e32 v0, v176, v0
	s_waitcnt lgkmcnt(6)
	v_mfma_f32_32x32x16_bf16 v[34:49], v[202:205], v[86:89], v[34:49]
	v_add_f32_e32 v0, v177, v0
	v_add_f32_e32 v0, v179, v0
	ds_read_b128 v[198:201], v150 offset:22080
	ds_read_b128 v[202:205], v150 offset:22112
	s_waitcnt lgkmcnt(7)
	v_mfma_f32_32x32x16_bf16 v[66:81], v[206:209], v[82:85], v[66:81]
	v_add_f32_e32 v0, v90, v0
	v_add_f32_e32 v0, v91, v0
	s_waitcnt lgkmcnt(6)
	v_mfma_f32_32x32x16_bf16 v[66:81], v[210:213], v[86:89], v[66:81]
	v_add_f32_e32 v0, v92, v0
	v_add_f32_e32 v0, v93, v0
	ds_read_b128 v[206:209], v150 offset:26688
	ds_read_b128 v[210:213], v150 offset:26720
	s_waitcnt lgkmcnt(7)
	v_mfma_f32_32x32x16_bf16 v[50:65], v[236:239], v[82:85], v[50:65]
	v_add_f32_e32 v0, v94, v0
	v_add_f32_e32 v0, v95, v0
	s_waitcnt lgkmcnt(6)
	v_mfma_f32_32x32x16_bf16 v[50:65], v[240:243], v[86:89], v[50:65]
	v_add_f32_e32 v0, v96, v0
	v_add_f32_e32 v0, v97, v0
	ds_read_b128 v[236:239], v150 offset:31296
	ds_read_b128 v[240:243], v150 offset:31328
	v_exp_f32_e32 v181, v220
	v_exp_f32_e32 v197, v221
	v_exp_f32_e32 v214, v222
	v_exp_f32_e32 v244, v223
	v_exp_f32_e32 v245, v224
	v_exp_f32_e32 v246, v225
	v_exp_f32_e32 v247, v226
	v_exp_f32_e32 v248, v227
	v_exp_f32_e32 v228, v228
	v_exp_f32_e32 v229, v229
	v_exp_f32_e32 v230, v230
	v_exp_f32_e32 v231, v231
	v_exp_f32_e32 v232, v232
	v_exp_f32_e32 v233, v233
	v_exp_f32_e32 v234, v234
	v_exp_f32_e32 v235, v235
	v_cvt_pk_bf16_f32 v220, v181, v197
	v_cvt_pk_bf16_f32 v221, v214, v244
	v_cvt_pk_bf16_f32 v222, v245, v246
	v_cvt_pk_bf16_f32 v223, v247, v248
	v_cvt_pk_bf16_f32 v224, v228, v229
	v_cvt_pk_bf16_f32 v225, v230, v231
	v_cvt_pk_bf16_f32 v226, v232, v233
	v_cvt_pk_bf16_f32 v227, v234, v235
	s_waitcnt lgkmcnt(7)
	v_mfma_f32_32x32x16_bf16 v[18:33], v[130:133], v[220:223], v[18:33]
	v_add_f32_e32 v0, v181, v0
	v_add_f32_e32 v0, v197, v0
	s_waitcnt lgkmcnt(6)
	v_mfma_f32_32x32x16_bf16 v[18:33], v[182:185], v[224:227], v[18:33]
	v_add_f32_e32 v0, v214, v0
	v_add_f32_e32 v0, v244, v0
	s_waitcnt lgkmcnt(5)
	v_mfma_f32_32x32x16_bf16 v[34:49], v[198:201], v[220:223], v[34:49]
	v_add_f32_e32 v0, v245, v0
	v_add_f32_e32 v0, v246, v0
	s_waitcnt lgkmcnt(4)
	v_mfma_f32_32x32x16_bf16 v[34:49], v[202:205], v[224:227], v[34:49]
	v_add_f32_e32 v0, v247, v0
	v_add_f32_e32 v0, v248, v0
	s_waitcnt lgkmcnt(3)
	v_mfma_f32_32x32x16_bf16 v[66:81], v[206:209], v[220:223], v[66:81]
	v_add_f32_e32 v0, v228, v0
	v_add_f32_e32 v0, v229, v0
	s_waitcnt lgkmcnt(2)
	v_mfma_f32_32x32x16_bf16 v[66:81], v[210:213], v[224:227], v[66:81]
	v_add_f32_e32 v0, v230, v0
	v_add_f32_e32 v0, v231, v0
	s_waitcnt lgkmcnt(1)
	v_mfma_f32_32x32x16_bf16 v[50:65], v[236:239], v[220:223], v[50:65]
	v_add_f32_e32 v0, v232, v0
	v_add_f32_e32 v0, v233, v0
	s_waitcnt lgkmcnt(0)
	v_mfma_f32_32x32x16_bf16 v[50:65], v[240:243], v[224:227], v[50:65]
	v_add_f32_e32 v0, v234, v0
	v_add_f32_e32 v0, v235, v0
; #define ATT_QK(SX, sub) do { __builtin_amdgcn_s_setprio(1); _Pragma("unroll") for (int ks = 0; ks < 4; ++ks) { \
;             const bf16x8 kf = *(LAS const bf16x8*)(Bb + KOFF + ((sub) * 32 + r) * 272 + (c * 64 + 16 * ks + 8 * h) * 2); SX = MFMA32(kf, qf[ks], SX); } __builtin_amdgcn_s_setprio(0); } while (0)
; #define ATT_SOFT(SX, P0, P1) do { float p[16]; _Pragma("unroll") for (int i = 0; i < 16; ++i) { p[i] = __builtin_amdgcn_exp2f(SX[i]); lsum += p[i]; } \
;             P0 = pk8f(p[0], p[1], p[2], p[3], p[4], p[5], p[6], p[7]); P1 = pk8f(p[8], p[9], p[10], p[11], p[12], p[13], p[14], p[15]); } while (0)
; #define ATT_PV(sub, P0, P1) do { __builtin_amdgcn_s_setprio(1); _Pragma("unroll") for (int et = 0; et < 4; ++et) { _Pragma("unroll") for (int s = 0; s < 2; ++s) { \
;             const bf16x8 vf = *(LAS const bf16x8*)(Bb + VOFF + (et * 32 + r) * 144 + ((sub) * 32 + 16 * s + 8 * h) * 2); O[et] = MFMA32(vf, s ? P1 : P0, O[et]); } } __builtin_amdgcn_s_setprio(0); } while (0)
; __device__ __forceinline__ void attn_unit(const TI ti, CArgs& a, int b, int hd, int qrow0, int st_lo, int st_hi, float mfix, float lam, float lam_init, const float* subg, unsigned char* ldsg) {
;     ...
;         } else {
;             ATT_QK(Sx0, 0);
;             __builtin_amdgcn_sched_barrier(0);
;             ATT_SOFT(Sx0, pa0, pa1);
;             __builtin_amdgcn_sched_barrier(0);
;             ATT_QK(Sx1, 1); ATT_PV(0, pa0, pa1);
;             __builtin_amdgcn_sched_barrier(0);
;             ATT_SOFT(Sx1, pc0, pc1); ATT_PV(1, pc0, pc1);
;         }
.LBB0_354:
	s_andn2_saveexec_b64 s[4:5], s[4:5]
	s_cbranch_execz .LBB0_351
	ds_read_b128 v[182:185], v151 offset:32
	ds_read_b128 v[198:201], v151 offset:64
	ds_read_b128 v[202:205], v151 offset:96
	ds_read_b128 v[206:209], v151 offset:8704
	ds_read_b128 v[210:213], v151 offset:8736
	ds_read_b128 v[236:239], v151 offset:8768
	ds_read_b128 v[240:243], v151 offset:8800
	s_waitcnt lgkmcnt(7)
	v_mfma_f32_32x32x16_bf16 v[82:97], v[130:133], v[110:113], v[2:17]
	s_waitcnt lgkmcnt(6)
	v_mfma_f32_32x32x16_bf16 v[82:97], v[182:185], v[106:109], v[82:97]
	s_waitcnt lgkmcnt(5)
	v_mfma_f32_32x32x16_bf16 v[82:97], v[198:201], v[102:105], v[82:97]
	s_waitcnt lgkmcnt(4)
	v_mfma_f32_32x32x16_bf16 v[82:97], v[202:205], v[98:101], v[82:97]
	ds_read_b128 v[130:133], v150 offset:17408
	ds_read_b128 v[182:185], v150 offset:17440
	ds_read_b128 v[198:201], v150 offset:22016
	ds_read_b128 v[202:205], v150 offset:22048
	s_nop 6
	v_exp_f32_e32 v169, v82
	v_exp_f32_e32 v170, v83
	v_exp_f32_e32 v171, v84
	v_exp_f32_e32 v174, v85
	v_exp_f32_e32 v175, v86
	v_exp_f32_e32 v176, v87
	v_exp_f32_e32 v177, v88
	v_exp_f32_e32 v179, v89
	v_exp_f32_e32 v90, v90
	v_exp_f32_e32 v91, v91
	v_exp_f32_e32 v92, v92
	v_exp_f32_e32 v93, v93
	v_exp_f32_e32 v94, v94
	v_exp_f32_e32 v95, v95
	v_exp_f32_e32 v96, v96
	v_exp_f32_e32 v97, v97
	v_cvt_pk_bf16_f32 v82, v169, v170
	v_cvt_pk_bf16_f32 v83, v171, v174
	v_cvt_pk_bf16_f32 v84, v175, v176
	v_cvt_pk_bf16_f32 v85, v177, v179
	v_cvt_pk_bf16_f32 v86, v90, v91
	v_cvt_pk_bf16_f32 v87, v92, v93
	v_cvt_pk_bf16_f32 v88, v94, v95
	v_cvt_pk_bf16_f32 v89, v96, v97
	s_waitcnt lgkmcnt(7)
	v_mfma_f32_32x32x16_bf16 v[220:235], v[206:209], v[110:113], v[2:17]
	s_waitcnt lgkmcnt(6)
	v_mfma_f32_32x32x16_bf16 v[220:235], v[210:213], v[106:109], v[220:235]
	s_waitcnt lgkmcnt(5)
	v_mfma_f32_32x32x16_bf16 v[220:235], v[236:239], v[102:105], v[220:235]
	s_waitcnt lgkmcnt(4)
	v_mfma_f32_32x32x16_bf16 v[220:235], v[240:243], v[98:101], v[220:235]
	ds_read_b128 v[206:209], v150 offset:26624
	ds_read_b128 v[210:213], v150 offset:26656
	ds_read_b128 v[236:239], v150 offset:31232
	ds_read_b128 v[240:243], v150 offset:31264
	s_waitcnt lgkmcnt(7)
	v_mfma_f32_32x32x16_bf16 v[18:33], v[130:133], v[82:85], v[18:33]
	v_add_f32_e32 v0, v169, v0
	v_add_f32_e32 v0, v170, v0
	s_waitcnt lgkmcnt(6)
	v_mfma_f32_32x32x16_bf16 v[18:33], v[182:185], v[86:89], v[18:33]
	v_add_f32_e32 v0, v171, v0
	v_add_f32_e32 v0, v174, v0
	ds_read_b128 v[130:133], v150 offset:17472
	ds_read_b128 v[182:185], v150 offset:17504
	s_waitcnt lgkmcnt(7)
	v_mfma_f32_32x32x16_bf16 v[34:49], v[198:201], v[82:85], v[34:49]
	v_add_f32_e32 v0, v175, v0
	v_add_f32_e32 v0, v176, v0
	s_waitcnt lgkmcnt(6)
	v_mfma_f32_32x32x16_bf16 v[34:49], v[202:205], v[86:89], v[34:49]
	v_add_f32_e32 v0, v177, v0
	v_add_f32_e32 v0, v179, v0
	ds_read_b128 v[198:201], v150 offset:22080
	ds_read_b128 v[202:205], v150 offset:22112
	s_waitcnt lgkmcnt(7)
	v_mfma_f32_32x32x16_bf16 v[66:81], v[206:209], v[82:85], v[66:81]
	v_add_f32_e32 v0, v90, v0
	v_add_f32_e32 v0, v91, v0
	s_waitcnt lgkmcnt(6)
	v_mfma_f32_32x32x16_bf16 v[66:81], v[210:213], v[86:89], v[66:81]
	v_add_f32_e32 v0, v92, v0
	v_add_f32_e32 v0, v93, v0
	ds_read_b128 v[206:209], v150 offset:26688
	ds_read_b128 v[210:213], v150 offset:26720
	s_waitcnt lgkmcnt(7)
	v_mfma_f32_32x32x16_bf16 v[50:65], v[236:239], v[82:85], v[50:65]
	v_add_f32_e32 v0, v94, v0
	v_add_f32_e32 v0, v95, v0
	s_waitcnt lgkmcnt(6)
	v_mfma_f32_32x32x16_bf16 v[50:65], v[240:243], v[86:89], v[50:65]
	v_add_f32_e32 v0, v96, v0
	v_add_f32_e32 v0, v97, v0
	ds_read_b128 v[236:239], v150 offset:31296
	ds_read_b128 v[240:243], v150 offset:31328
	v_exp_f32_e32 v181, v220
	v_exp_f32_e32 v197, v221
	v_exp_f32_e32 v214, v222
	v_exp_f32_e32 v244, v223
	v_exp_f32_e32 v245, v224
	v_exp_f32_e32 v246, v225
	v_exp_f32_e32 v247, v226
	v_exp_f32_e32 v248, v227
	v_exp_f32_e32 v228, v228
	v_exp_f32_e32 v229, v229
	v_exp_f32_e32 v230, v230
	v_exp_f32_e32 v231, v231
	v_exp_f32_e32 v232, v232
	v_exp_f32_e32 v233, v233
	v_exp_f32_e32 v234, v234
	v_exp_f32_e32 v235, v235
	v_cvt_pk_bf16_f32 v220, v181, v197
	v_cvt_pk_bf16_f32 v221, v214, v244
	v_cvt_pk_bf16_f32 v222, v245, v246
	v_cvt_pk_bf16_f32 v223, v247, v248
	v_cvt_pk_bf16_f32 v224, v228, v229
	v_cvt_pk_bf16_f32 v225, v230, v231
	v_cvt_pk_bf16_f32 v226, v232, v233
	v_cvt_pk_bf16_f32 v227, v234, v235
	s_waitcnt lgkmcnt(7)
	v_mfma_f32_32x32x16_bf16 v[18:33], v[130:133], v[220:223], v[18:33]
	v_add_f32_e32 v0, v181, v0
	v_add_f32_e32 v0, v197, v0
	s_waitcnt lgkmcnt(6)
	v_mfma_f32_32x32x16_bf16 v[18:33], v[182:185], v[224:227], v[18:33]
	v_add_f32_e32 v0, v214, v0
	v_add_f32_e32 v0, v244, v0
	s_waitcnt lgkmcnt(5)
	v_mfma_f32_32x32x16_bf16 v[34:49], v[198:201], v[220:223], v[34:49]
	v_add_f32_e32 v0, v245, v0
	v_add_f32_e32 v0, v246, v0
	s_waitcnt lgkmcnt(4)
	v_mfma_f32_32x32x16_bf16 v[34:49], v[202:205], v[224:227], v[34:49]
	v_add_f32_e32 v0, v247, v0
	v_add_f32_e32 v0, v248, v0
	s_waitcnt lgkmcnt(3)
	v_mfma_f32_32x32x16_bf16 v[66:81], v[206:209], v[220:223], v[66:81]
	v_add_f32_e32 v0, v228, v0
	v_add_f32_e32 v0, v229, v0
	s_waitcnt lgkmcnt(2)
	v_mfma_f32_32x32x16_bf16 v[66:81], v[210:213], v[224:227], v[66:81]
	v_add_f32_e32 v0, v230, v0
	v_add_f32_e32 v0, v231, v0
	s_waitcnt lgkmcnt(1)
	v_mfma_f32_32x32x16_bf16 v[50:65], v[236:239], v[220:223], v[50:65]
	v_add_f32_e32 v0, v232, v0
	v_add_f32_e32 v0, v233, v0
	s_waitcnt lgkmcnt(0)
	v_mfma_f32_32x32x16_bf16 v[50:65], v[240:243], v[224:227], v[50:65]
	v_add_f32_e32 v0, v234, v0
	v_add_f32_e32 v0, v235, v0
	s_branch .LBB0_351
